# stack A + compressed-branch tiles 0,1 of the next unit prefetched during the window branch (cmp prologue wait removed)
# speedup vs baseline: 1.0349x; 1.0012x over previous
.LBB0_984:
	s_add_u32 s3, s92, 0x3600000
	s_addc_u32 s52, s93, 0
	s_add_u32 s53, s92, 0x3680000
	s_addc_u32 s54, s93, 0
	v_lshrrev_b32_e32 v5, 3, v129
	s_add_u32 s55, s92, 0xc000000
	v_lshlrev_b32_e32 v2, 3, v129
	v_mul_u32_u24_e32 v7, 0x50, v5
	v_lshlrev_b32_e32 v8, 4, v129
	s_addc_u32 s56, s93, 0
	v_and_b32_e32 v2, 56, v2
	v_lshl_add_u32 v7, v7, 1, 0
	v_and_b32_e32 v8, 64, v8
	s_add_u32 s57, s92, 0xc800000
	v_lshl_add_u32 v151, v2, 1, v7
	v_add_u32_e32 v7, v7, v8
	v_lshlrev_b32_e32 v8, 5, v129
	v_lshlrev_b32_e32 v9, 2, v129
	s_addc_u32 s60, s93, 0
	v_and_b32_e32 v8, 32, v8
	v_and_b32_e32 v9, 8, v9
	s_add_u32 s38, s92, 0x14000000
	v_add3_u32 v152, v7, v8, v9
	v_and_b32_e32 v7, 48, v129
	v_mul_u32_u24_e32 v8, 0xa0, v130
	s_addc_u32 s39, s93, 0
	s_waitcnt lgkmcnt(0)
	v_mul_u32_u24_e32 v1, 0x2100, v131
	s_add_i32 s0, 0, 0x14000
	v_add3_u32 v153, 0, v7, v8
	v_mul_u32_u24_e32 v8, 0x210, v130
	v_add3_u32 v154, s0, v1, v8
	v_lshlrev_b64 v[8:9], v128, -1
	v_lshlrev_b32_e32 v0, 3, v68
	v_lshl_or_b32 v12, v131, 1, 1
	v_not_b32_e32 v125, v9
	v_lshlrev_b32_e32 v9, 5, v131
	v_lshlrev_b32_e32 v14, 4, v12
	v_lshlrev_b32_e32 v132, 1, v0
	v_add_u32_e32 v0, 0, v9
	s_add_i32 s1, 0, 0x24b10
	s_movk_i32 s20, 0x210
	v_add_u32_e32 v175, 0x24800, v0
	v_add_u32_e32 v0, 0, v14
	s_cmpk_eq_i32 s84, 0x100
	v_add_u32_e32 v7, 48, v129
	v_lshlrev_b32_e32 v124, 2, v68
	v_lshlrev_b32_e32 v10, 2, v128
	v_not_b32_e32 v126, v8
	v_lshrrev_b32_e32 v8, 5, v129
	v_mad_u32_u24 v1, v130, s20, v1
	v_add_u32_e32 v176, 0x24800, v0
	v_mbcnt_lo_u32_b32 v0, -1, 0
	s_cselect_b64 s[42:43], -1, 0
	s_ashr_i32 s4, s2, 3
	v_lshlrev_b32_e32 v150, 6, v68
	v_and_b32_e32 v7, 63, v7
	v_add_u32_e32 v13, s0, v10
	s_add_i32 s0, 0, 0x24800
	v_cmp_eq_u32_e64 s[12:13], 1, v8
	v_cmp_eq_u32_e64 s[14:15], 2, v8
	v_lshlrev_b32_e64 v8, v129, -1
	v_or_b32_e32 v1, v1, v124
	v_mbcnt_hi_u32_b32 v180, -1, v0
	v_lshl_add_u32 v3, v130, 2, s1
	s_mul_i32 s61, s4, -7
	s_mul_i32 s62, s4, 7
	v_lshlrev_b32_e32 v4, 6, v5
	v_lshlrev_b32_e32 v6, 9, v5
	v_and_b32_e32 v11, 0x3c0, v129
	v_add_u32_e32 v157, s0, v10
	s_movk_i32 s8, 0x80
	s_movk_i32 s18, 0x5f
	v_not_b32_e32 v159, v8
	v_lshlrev_b32_e32 v8, 11, v5
	v_lshlrev_b32_e32 v10, 13, v5
	v_lshl_add_u32 v161, v131, 3, s1
	v_mul_u32_u24_e32 v5, 0x420, v131
	v_mul_u32_u24_e32 v12, 0x210, v12
	v_sub_u32_e32 v15, v130, v150
	v_add_u32_e32 v170, 0, v1
	v_sub_u32_e32 v1, v130, v124
	s_mov_b32 s44, 2.0
	v_and_or_b32 v0, v180, 64, v7
	s_mov_b32 s41, 0
	s_addk_i32 s61, 0x208
	s_add_i32 s62, s62, 62
	s_lshl_b32 s63, s4, 1
	v_mov_b32_e32 v123, 0
	v_cmp_gt_u32_e64 s[4:5], 16, v128
	v_add_u32_e32 v155, v154, v124
	v_or_b32_e32 v156, 64, v128
	v_cmp_eq_u32_e64 s[6:7], 0, v128
	v_cmp_gt_u32_e64 s[8:9], s8, v129
	v_cmp_gt_u32_e64 s[10:11], 32, v129
	v_lshlrev_b32_e64 v158, v129, 1
	v_cmp_lt_u32_e64 s[16:17], 63, v129
	v_cmp_lt_u32_e64 s[18:19], s18, v129
	v_lshl_add_u32 v160, v130, 4, s0
	v_add_u32_e32 v162, 64, v161
	v_add_u32_e32 v163, 0x80, v161
	v_add_u32_e32 v164, 0xc0, v161
	v_add_u32_e32 v165, 0x100, v161
	v_add_u32_e32 v166, 0x140, v161
	v_add_u32_e32 v167, 0x180, v161
	v_add_u32_e32 v168, 0x1c0, v161
	v_mov_b32_e32 v127, v128
	v_add_u32_e32 v169, 0xfffffcb1, v15
	v_add_u32_e32 v171, 0xffffff8d, v1
	s_mov_b32 s64, 0xc2fc0000
	v_lshlrev_b32_e32 v134, 1, v4
	v_lshlrev_b32_e32 v136, 1, v6
	s_mov_b32 s65, 0x42000000
	s_mov_b32 s66, 0x42400000
	s_mov_b32 s67, 0x43800000
	s_brev_b32 s68, 34
	s_mov_b32 s69, 0x44400000
	s_mov_b32 s45, 0x3e38aa3b
	s_brev_b32 s70, -2
	s_movk_i32 s71, 0x200
	v_add_u32_e32 v172, v3, v11
	v_add_u32_e32 v173, v13, v5
	v_add_u32_e32 v174, v13, v12
	s_add_i32 s72, 0, 0x24900
	v_lshlrev_b32_e32 v138, 1, v8
	v_lshlrev_b32_e32 v122, 1, v2
	v_lshlrev_b32_e32 v140, 1, v10
	s_mov_b32 s46, 0x40400000
	s_mov_b32 s28, 0x3f803f80
	v_mov_b32_e32 v142, 0x41800000
	v_mov_b32_e32 v177, 0x42800000
	v_not_b32_e32 v178, 63
	v_mov_b32_e32 v179, 0xff800000
	v_lshlrev_b32_e32 v181, 2, v0
	v_mov_b32_e32 v182, 0x7f000000
	s_mov_b32 s22, s2
	s_ashr_i32 s90, s2, 3
	s_add_i32 s98, s90, -1
	s_ashr_i32 s98, s98, 6
	s_cmp_gt_i32 s98, 0
	s_cselect_b32 s99, 0x2000, 0
	s_cselect_b32 s98, 0x80, 0
	s_and_b32 s29, s2, 3
	s_lshl_b32 s29, s29, 1
	s_bfe_u32 s30, s2, 0x10002
	s_or_b32 s29, s29, s30
	s_lshl_b32 s29, s29, 16
	s_add_u32 s100, s3, s29
	s_addc_u32 s101, s52, 0
	s_add_u32 s30, s53, s29
	s_addc_u32 s31, s54, 0
	v_mov_b32_e32 v194, v134
	v_mov_b32_e32 v195, 0
	v_mov_b32_e32 v196, v136
	v_mov_b32_e32 v197, 0
	v_lshl_add_u64 v[198:199], s[100:101], 0, v[194:195]
	v_lshl_add_u64 v[200:201], s[30:31], 0, v[196:197]
	v_lshl_add_u64 v[198:199], v[198:199], 0, v[122:123]
	v_lshl_add_u64 v[200:201], v[200:201], 0, v[122:123]
	global_load_dwordx4 v[240:243], v[198:199], off
	global_load_dwordx4 v[244:247], v[200:201], off
	s_add_u32 s100, s100, s99
	s_addc_u32 s101, s101, 0
	s_add_u32 s30, s30, s98
	s_addc_u32 s31, s31, 0
	v_lshl_add_u64 v[198:199], s[100:101], 0, v[194:195]
	v_lshl_add_u64 v[200:201], s[30:31], 0, v[196:197]
	v_lshl_add_u64 v[198:199], v[198:199], 0, v[122:123]
	v_lshl_add_u64 v[200:201], v[200:201], 0, v[122:123]
	global_load_dwordx4 v[248:251], v[198:199], off
	global_load_dwordx4 v[252:255], v[200:201], off
	s_waitcnt vmcnt(0)
	s_branch .LBB0_987

.LBB0_1007:
	s_mov_b32 s90, s20
	s_lshl_b32 s0, s23, 13
	s_lshl_b32 s1, s20, 4
	s_and_b32 s40, s22, 3
	s_bfe_u32 s29, s22, 0x10002
	s_lshl_b32 s74, s75, 4
	s_and_b32 s0, s0, 0x6000
	s_ashr_i32 s20, s1, 31
	s_add_u32 s0, s1, s0
	s_addc_u32 s1, s20, 0
	v_or_b32_e32 v0, s0, v130
	s_lshl_b32 s0, s23, 1
	v_mov_b32_e32 v1, s1
	s_and_b32 s0, s0, 8
	v_add_u32_e32 v4, s0, v131
	v_lshlrev_b64 v[0:1], 12, v[0:1]
	v_lshl_add_u64 v[0:1], s[36:37], 0, v[0:1]
	v_lshlrev_b32_e32 v2, 7, v4
	v_mov_b32_e32 v3, v123
	v_lshl_add_u64 v[2:3], v[0:1], 0, v[2:3]
	v_mov_b32_e32 v133, v123
	v_lshl_add_u64 v[2:3], v[2:3], 0, v[132:133]
	global_load_dwordx4 v[48:51], v[2:3], off
	global_load_dwordx4 v[52:55], v[2:3], off offset:64
	v_mul_u32_u24_e32 v2, 3, v4
	v_lshlrev_b32_e32 v2, 1, v2
	v_mov_b32_e32 v3, v123
	v_lshl_add_u64 v[0:1], v[0:1], 0, v[2:3]
	global_load_dword v133, v[0:1], off offset:3584
	global_load_ushort v185, v[0:1], off offset:3588
	v_lshl_add_u32 v184, s29, 3, v131
	v_add_u32_e32 v0, 1, v184
	v_cvt_f32_ubyte0_e32 v0, v0
	v_mul_f32_e32 v1, -0.5, v0
	v_cmp_gt_f32_e32 vcc, s64, v1
	s_lshl_b32 s0, s40, 1
	s_or_b32 s47, s0, s29
	v_cndmask_b32_e32 v1, 0, v177, vcc
	v_fmac_f32_e32 v1, -0.5, v0
	v_exp_f32_e32 v0, v1
	s_add_i32 s0, s75, -1
	s_ashr_i32 s0, s0, 6
	s_add_i32 s0, s0, 1
	v_cndmask_b32_e32 v1, 0, v178, vcc
	s_cmp_gt_i32 s75, 0
	v_ldexp_f32 v0, v0, v1
	s_cselect_b32 s20, s0, 0
	v_mov_b32_e32 v75, 0
	v_mul_f32_e32 v146, 0x3fb8aa3b, v0
	v_or_b32_e32 v144, s74, v130
	s_cmp_lt_i32 s20, 1
	v_add_u32_e32 v187, 0xa000, v152
	v_add_u32_e32 v186, 0xc800, v152
	v_mov_b32_e32 v74, 0
	v_mov_b32_e32 v73, 0
	v_mov_b32_e32 v72, 0
	v_mov_b32_e32 v79, 0
	v_mov_b32_e32 v78, 0
	v_mov_b32_e32 v77, 0
	v_mov_b32_e32 v76, 0
	v_mov_b32_e32 v71, 0
	v_mov_b32_e32 v70, 0
	v_mov_b32_e32 v69, 0
	v_mov_b32_e32 v68, 0
	v_mov_b32_e32 v67, 0
	v_mov_b32_e32 v66, 0
	v_mov_b32_e32 v65, 0
	v_mov_b32_e32 v64, 0
	v_mov_b32_e32 v80, 0
	v_mov_b32_e32 v81, 0
	s_cbranch_scc1 .LBB0_1027
	s_lshl_b32 s21, s47, 16
	s_add_u32 s0, s3, s21
	s_addc_u32 s1, s52, 0
	s_add_u32 s22, s53, s21
	s_addc_u32 s23, s54, 0
	s_add_i32 s21, s20, -1
	s_cmp_eq_u32 s20, 1
	s_cselect_b64 s[24:25], -1, 0
	s_and_b64 vcc, s[24:25], exec
	s_cselect_b32 s26, 0, 64
	s_lshl_b32 s24, s26, 7
	v_mov_b32_e32 v135, v123
	s_add_u32 s24, s0, s24
	v_lshl_add_u64 v[0:1], s[0:1], 0, v[134:135]
	v_mov_b32_e32 v137, v123
	s_addc_u32 s25, s1, 0
	s_lshl_b32 s26, s26, 1
	v_lshl_add_u64 v[44:45], v[0:1], 0, v[122:123]
	v_lshl_add_u64 v[0:1], s[22:23], 0, v[136:137]
	s_add_u32 s26, s22, s26
	v_lshl_add_u64 v[46:47], v[0:1], 0, v[122:123]
	s_addc_u32 s27, s23, 0
	v_lshl_add_u64 v[0:1], s[24:25], 0, v[134:135]
	v_mov_b32_e32 v8, v240
	v_mov_b32_e32 v9, v241
	v_mov_b32_e32 v10, v242
	v_mov_b32_e32 v11, v243
	v_mov_b32_e32 v12, v244
	v_mov_b32_e32 v13, v245
	v_mov_b32_e32 v14, v246
	v_mov_b32_e32 v15, v247
	v_lshl_add_u64 v[0:1], v[0:1], 0, v[122:123]
	v_lshl_add_u64 v[2:3], s[26:27], 0, v[136:137]
	v_lshl_add_u64 v[2:3], v[2:3], 0, v[122:123]
	v_mov_b32_e32 v16, v248
	v_mov_b32_e32 v17, v249
	v_mov_b32_e32 v18, v250
	v_mov_b32_e32 v19, v251
	v_mov_b32_e32 v20, v252
	v_mov_b32_e32 v21, v253
	v_mov_b32_e32 v22, v254
	v_mov_b32_e32 v23, v255
	s_min_u32 s26, s21, 2
	s_lshl_b32 s24, s26, 13
	s_add_u32 s24, s0, s24
	s_addc_u32 s25, s1, 0
	s_lshl_b32 s26, s26, 7
	s_add_u32 s26, s22, s26
	v_lshl_add_u64 v[0:1], s[24:25], 0, v[134:135]
	s_addc_u32 s27, s23, 0
	s_min_u32 s24, s21, 3
	s_lshl_b32 s25, s24, 13
	s_add_u32 s0, s0, s25
	v_lshl_add_u64 v[2:3], s[26:27], 0, v[136:137]
	s_addc_u32 s1, s1, 0
	s_lshl_b32 s24, s24, 7
	v_lshl_add_u64 v[0:1], v[0:1], 0, v[122:123]
	v_lshl_add_u64 v[2:3], v[2:3], 0, v[122:123]
	s_add_u32 s22, s22, s24
	global_load_dwordx4 v[4:7], v[0:1], off
	s_nop 0
	global_load_dwordx4 v[0:3], v[2:3], off
	v_lshl_add_u64 v[24:25], s[0:1], 0, v[134:135]
	s_addc_u32 s23, s23, 0
	v_lshl_add_u64 v[24:25], v[24:25], 0, v[122:123]
	v_lshl_add_u64 v[26:27], s[22:23], 0, v[136:137]
	v_lshl_add_u64 v[26:27], v[26:27], 0, v[122:123]
	v_mov_b32_e32 v75, 0
	s_mov_b32 s0, 0
	v_mov_b32_e32 v74, v75
	v_mov_b32_e32 v73, v75
	v_mov_b32_e32 v72, v75
	v_mov_b32_e32 v79, v75
	v_mov_b32_e32 v78, v75
	v_mov_b32_e32 v77, v75
	v_mov_b32_e32 v76, v75
	v_mov_b32_e32 v71, v75
	v_mov_b32_e32 v70, v75
	v_mov_b32_e32 v69, v75
	v_mov_b32_e32 v68, v75
	v_mov_b32_e32 v67, v75
	v_mov_b32_e32 v66, v75
	v_mov_b32_e32 v65, v75
	v_mov_b32_e32 v64, v75
	v_mov_b32_e32 v80, v75
	v_mov_b32_e32 v81, v75
	ds_write_b128 v151, v[8:11]
	ds_write2_b64 v187, v[12:13], v[14:15] offset1:2
	ds_write_b128 v151, v[16:19] offset:10240
	ds_write2_b64 v186, v[20:21], v[22:23] offset1:2
	global_load_dwordx4 v[12:15], v[24:25], off
	global_load_dwordx4 v[8:11], v[26:27], off
	s_waitcnt lgkmcnt(0)
	s_barrier
	s_cbranch_vccnz .LBB0_1021
	v_mov_b32_e32 v80, 0
	s_add_i32 s22, s75, -2
	v_mul_f32_e32 v82, 0x41800000, v146
	v_mul_f32_e32 v83, 0x42000000, v146
	v_mul_f32_e32 v84, 0x42400000, v146
	v_mul_f32_e32 v85, 0, v146
	s_waitcnt lgkmcnt(7)
	v_mul_f32_e32 v86, 0x43800000, v146
	v_mul_f32_e32 v87, 0x44000000, v146
	v_mul_f32_e32 v88, 0x44400000, v146
	v_add_u32_e32 v89, s74, v169
	s_mov_b32 s24, 5
	s_movk_i32 s23, 0xc0
	v_mov_b32_e32 v81, 0
	v_mov_b32_e32 v64, 0
	v_mov_b32_e32 v65, v80
	v_mov_b32_e32 v66, v80
	v_mov_b32_e32 v67, v80
	v_mov_b32_e32 v68, 0
	v_mov_b32_e32 v69, v80
	v_mov_b32_e32 v70, v80
	v_mov_b32_e32 v71, v80
	v_mov_b32_e32 v76, 0
	v_mov_b32_e32 v77, v80
	v_mov_b32_e32 v78, v80
	v_mov_b32_e32 v79, v80
	v_mov_b32_e32 v72, 0
	v_mov_b32_e32 v73, v80
	v_mov_b32_e32 v74, v80
	v_mov_b32_e32 v75, v80

.LBB0_1059:
	s_lshl_b32 s0, s80, 1
	s_add_u32 s0, s57, s0
	s_addc_u32 s1, s60, 0
	s_add_i32 s20, s74, 0xfffffe01
	s_andn2_b32 s20, s20, 63
	s_cmp_gt_i32 s75, 31
	s_cselect_b32 s20, s20, 0
	s_sub_i32 s21, s74, s20
	s_ashr_i32 s21, s21, 6
	s_min_i32 s22, s21, 0
	s_lshl_b32 s22, s22, 6
	s_add_i32 s22, s22, s20
	s_ashr_i32 s23, s22, 31
	s_lshl_b64 s[26:27], s[22:23], 12
	s_add_u32 s26, s24, s26
	s_addc_u32 s27, s25, s27
	s_lshl_b64 s[22:23], s[22:23], 1
	s_add_u32 s22, s0, s22
	s_addc_u32 s23, s1, s23
	v_mov_b32_e32 v141, v123
	s_waitcnt vmcnt(2)
	v_lshl_add_u64 v[18:19], s[22:23], 0, v[140:141]
	s_min_i32 s22, s21, 1
	s_lshl_b32 s22, s22, 6
	s_add_i32 s22, s22, s20
	v_mov_b32_e32 v139, v123
	s_ashr_i32 s23, s22, 31
	v_lshl_add_u64 v[16:17], s[26:27], 0, v[138:139]
	s_lshl_b64 s[26:27], s[22:23], 12
	s_add_u32 s26, s24, s26
	s_addc_u32 s27, s25, s27
	s_lshl_b64 s[22:23], s[22:23], 1
	s_add_u32 s22, s0, s22
	s_addc_u32 s23, s1, s23
	v_lshl_add_u64 v[16:17], v[16:17], 0, v[122:123]
	v_lshl_add_u64 v[20:21], v[18:19], 0, v[122:123]
	s_waitcnt vmcnt(0)
	v_lshl_add_u64 v[24:25], s[26:27], 0, v[138:139]
	v_lshl_add_u64 v[26:27], s[22:23], 0, v[140:141]
	v_mov_b32_e32 v16, v240
	v_mov_b32_e32 v17, v241
	v_mov_b32_e32 v18, v242
	v_mov_b32_e32 v19, v243
	s_nop 0
	v_mov_b32_e32 v20, v244
	v_mov_b32_e32 v21, v245
	v_mov_b32_e32 v22, v246
	v_mov_b32_e32 v23, v247
	v_lshl_add_u64 v[24:25], v[24:25], 0, v[122:123]
	v_lshl_add_u64 v[28:29], v[26:27], 0, v[122:123]
	v_mov_b32_e32 v24, v248
	v_mov_b32_e32 v25, v249
	v_mov_b32_e32 v26, v250
	v_mov_b32_e32 v27, v251
	s_nop 0
	v_mov_b32_e32 v28, v252
	v_mov_b32_e32 v29, v253
	v_mov_b32_e32 v30, v254
	v_mov_b32_e32 v31, v255
	s_min_i32 s22, s21, 2
	s_lshl_b32 s22, s22, 6
	s_add_i32 s22, s22, s20
	s_ashr_i32 s23, s22, 31
	s_lshl_b64 s[26:27], s[22:23], 12
	s_add_u32 s26, s24, s26
	s_addc_u32 s27, s25, s27
	s_lshl_b64 s[22:23], s[22:23], 1
	s_add_u32 s22, s0, s22
	s_waitcnt lgkmcnt(3)
	v_lshl_add_u64 v[32:33], s[26:27], 0, v[138:139]
	s_addc_u32 s23, s1, s23
	s_min_i32 s26, s21, 3
	v_lshl_add_u64 v[34:35], s[22:23], 0, v[140:141]
	s_lshl_b32 s22, s26, 6
	s_add_i32 s22, s22, s20
	s_ashr_i32 s23, s22, 31
	s_lshl_b64 s[26:27], s[22:23], 12
	s_add_u32 s24, s24, s26
	s_addc_u32 s25, s25, s27
	s_lshl_b64 s[22:23], s[22:23], 1
	s_add_u32 s22, s0, s22
	v_lshl_add_u64 v[32:33], v[32:33], 0, v[122:123]
	v_lshl_add_u64 v[34:35], v[34:35], 0, v[122:123]
	s_addc_u32 s23, s1, s23
	s_waitcnt lgkmcnt(2)
	global_load_dwordx4 v[36:39], v[32:33], off offset:3072
	s_nop 0
	global_load_dwordx4 v[32:35], v[34:35], off
	s_waitcnt lgkmcnt(1)
	v_lshl_add_u64 v[40:41], s[24:25], 0, v[138:139]
	v_lshl_add_u64 v[42:43], s[22:23], 0, v[140:141]
	v_lshl_add_u64 v[40:41], v[40:41], 0, v[122:123]
	v_lshl_add_u64 v[42:43], v[42:43], 0, v[122:123]
	s_mov_b32 s23, 0
	s_cmp_lt_i32 s21, 1
	s_mov_b32 s24, 0
	s_waitcnt vmcnt(5)
	ds_write_b128 v151, v[16:19]
	s_waitcnt vmcnt(4)
	ds_write2_b64 v187, v[20:21], v[22:23] offset1:2
	s_waitcnt vmcnt(3)
	ds_write_b128 v151, v[24:27] offset:10240
	s_waitcnt vmcnt(2)
	ds_write2_b64 v186, v[28:29], v[30:31] offset1:2
	s_waitcnt lgkmcnt(4)
	global_load_dwordx4 v[44:47], v[40:41], off offset:3072
	s_nop 0
	global_load_dwordx4 v[40:43], v[42:43], off
	s_cselect_b32 s91, 1, 0
	s_add_i32 s98, s90, -1
	s_ashr_i32 s98, s98, 6
	s_cmp_gt_i32 s98, 0
	s_cselect_b32 s99, 0x2000, 0
	s_cselect_b32 s98, 0x80, 0
	s_and_b32 s29, s2, 3
	s_lshl_b32 s29, s29, 1
	s_bfe_u32 s30, s2, 0x10002
	s_or_b32 s29, s29, s30
	s_lshl_b32 s29, s29, 16
	s_add_u32 s100, s3, s29
	s_addc_u32 s101, s52, 0
	s_add_u32 s30, s53, s29
	s_addc_u32 s31, s54, 0
	v_mov_b32_e32 v194, v134
	v_mov_b32_e32 v195, 0
	v_mov_b32_e32 v196, v136
	v_mov_b32_e32 v197, 0
	v_lshl_add_u64 v[198:199], s[100:101], 0, v[194:195]
	v_lshl_add_u64 v[200:201], s[30:31], 0, v[196:197]
	v_lshl_add_u64 v[198:199], v[198:199], 0, v[122:123]
	v_lshl_add_u64 v[200:201], v[200:201], 0, v[122:123]
	global_load_dwordx4 v[240:243], v[198:199], off
	global_load_dwordx4 v[244:247], v[200:201], off
	s_add_u32 s100, s100, s99
	s_addc_u32 s101, s101, 0
	s_add_u32 s30, s30, s98
	s_addc_u32 s31, s31, 0
	v_lshl_add_u64 v[198:199], s[100:101], 0, v[194:195]
	v_lshl_add_u64 v[200:201], s[30:31], 0, v[196:197]
	v_lshl_add_u64 v[198:199], v[198:199], 0, v[122:123]
	v_lshl_add_u64 v[200:201], v[200:201], 0, v[122:123]
	global_load_dwordx4 v[248:251], v[198:199], off
	global_load_dwordx4 v[252:255], v[200:201], off
	s_cmp_lg_u32 s91, 0
	s_waitcnt lgkmcnt(0)
	s_barrier
	s_cbranch_scc1 .LBB0_1068
	v_lshl_add_u64 v[16:17], s[0:1], 0, v[140:141]
	v_lshl_add_u64 v[106:107], v[16:17], 0, v[122:123]
	v_add_u32_e32 v16, s74, v171
	v_mov_b32_e32 v86, 0
	s_add_i32 s22, s74, 0xfffffe10
	v_subrev_u32_e32 v81, s20, v16
	v_mov_b32_e32 v87, v86
	v_mov_b32_e32 v88, v86
	v_mov_b32_e32 v89, v86
	s_mov_b32 s23, 5
	v_mov_b32_e32 v90, v86
	v_mov_b32_e32 v91, v86
	v_mov_b32_e32 v92, v86
	v_mov_b32_e32 v93, v86
	v_mov_b32_e32 v94, v86
	v_mov_b32_e32 v95, v86
	v_mov_b32_e32 v96, v86
	v_mov_b32_e32 v97, v86
	v_mov_b32_e32 v98, v86
	v_mov_b32_e32 v99, v86
	v_mov_b32_e32 v100, v86
	v_mov_b32_e32 v101, v86
	v_mov_b32_e32 v102, v86
	v_mov_b32_e32 v103, v86
	v_mov_b32_e32 v104, v86
	v_mov_b32_e32 v105, v86
